# attention softmax: dropped the max(x,x) canonicalisations in the row-max reduction (34 fewer VALU per tile and wave), on top of the q-block swap and v_mov_b64 zeroing
# baseline (speedup 1.0000x reference)
; #define LAS __attribute__((address_space(3)))
; __device__ __forceinline__ int crow(int r, int hi) { return (r & 3) + 8 * (r >> 2) + 4 * hi; }
; #define MFMA32(a, b, c) __builtin_amdgcn_mfma_f32_32x32x16_bf16((a), (b), (c), 0, 0, 0)
; __device__ __forceinline__ void unit(LAS unsigned char* lds, const Tensors& T, int h, int qrow0, int nact, bool sample, int limbase, int kv0, int kvnew, int nt) {
;     ...
;         if (t + 1 < nt) ATT_ISSUE(t + 1);
;         if (active && t <= lim) {
;             const LAS unsigned char* kp = lds + OFF_K + buf * KBUF + r32 * KP + hi * 16;
;             f32x16 p0, p1;
; #pragma unroll
;             for (int r = 0; r < 16; ++r) { p0[r] = 0.f; p1[r] = 0.f; }
;             { bf16x8 kf[4][2];
; #pragma unroll
;               for (int i = 0; i < 4; ++i) { kf[i][0] = *(const LAS bf16x8*)(kp + i * 32); kf[i][1] = *(const LAS bf16x8*)(kp + 32 * KP + i * 32); }
;               __builtin_amdgcn_sched_barrier(0);
; #pragma unroll
;               for (int i = 0; i < 12; ++i) {
;                   p0 = MFMA32(kf[i & 3][0], qf[i], p0); p1 = MFMA32(kf[i & 3][1], qf[i], p1);
;                   if (i + 4 < 12) { kf[i & 3][0] = *(const LAS bf16x8*)(kp + (i + 4) * 32); kf[i & 3][1] = *(const LAS bf16x8*)(kp + 32 * KP + (i + 4) * 32); }
;                   __builtin_amdgcn_sched_barrier(0);
;               } }
;             float rm = fmaxf(p0[0], p1[0]);
; #pragma unroll
;             for (int r = 1; r < 16; ++r) rm = fmaxf(rm, fmaxf(p0[r], p1[r]));
;             { const auto rr = __builtin_amdgcn_permlane32_swap(__float_as_uint(rm), __float_as_uint(rm), false, false);
;               rm = fmaxf(__uint_as_float(rr[0]), __uint_as_float(rr[1])); }
;             const bool need = rm > mrun + 8.0f;
;             if (__builtin_amdgcn_ballot_w64(need) != 0ull) {
;                 const float mn = need ? rm : mrun; const float alpha = __builtin_amdgcn_exp2f(mrun - mn); mrun = mn; lrun *= alpha;
;                 if (hi == 0) scr[r32] = alpha;
;                 asm volatile("s_waitcnt lgkmcnt(0)" ::: "memory");
; #pragma unroll
;                 for (int r = 0; r < 16; ++r) { const float f = scr[crow(r, hi)];
; #pragma unroll
;                     for (int d = 0; d < 4; ++d) o[d][r] *= f; }
;                 asm volatile("s_waitcnt lgkmcnt(0)" ::: "memory");
;             }
.LBB0_904:
	global_load_dwordx4 v[160:163], v[198:199], off
	global_load_dwordx4 v[156:159], v[194:195], off
	global_load_dwordx4 v[152:155], v[192:193], off
	global_load_dwordx4 v[148:151], v[204:205], off
	global_load_dwordx4 v[144:147], v[202:203], off
	s_and_b32 s16, s9, 1
	s_cmp_gt_i32 s9, s10
	s_cselect_b64 s[0:1], -1, 0
	s_or_b64 s[0:1], s[22:23], s[0:1]
	s_and_b64 vcc, exec, s[0:1]
	s_cbranch_vccnz .LBB0_909
	s_mul_i32 s0, s16, 0x6400
	v_add_u32_e32 v222, s0, v221
	ds_read_b128 v[64:67], v222
	ds_read_b128 v[224:227], v222 offset:32
	ds_read_b128 v[68:71], v222 offset:12800
	ds_read_b128 v[228:231], v222 offset:12832
	ds_read_b128 v[232:235], v222 offset:64
	ds_read_b128 v[236:239], v222 offset:96
	ds_read_b128 v[240:243], v222 offset:12864
	ds_read_b128 v[244:247], v222 offset:12896
	s_waitcnt lgkmcnt(7)
	v_mfma_f32_32x32x16_bf16 v[80:95], v[64:67], v[140:143], 0
	ds_read_b128 v[248:251], v222 offset:128
	ds_read_b128 v[166:169], v222 offset:12928
	s_waitcnt lgkmcnt(7)
	v_mfma_f32_32x32x16_bf16 v[64:79], v[68:71], v[140:143], 0
	v_mfma_f32_32x32x16_bf16 v[80:95], v[224:227], v[136:139], v[80:95]
	s_waitcnt lgkmcnt(6)
	v_mfma_f32_32x32x16_bf16 v[64:79], v[228:231], v[136:139], v[64:79]
	ds_read_b128 v[224:227], v222 offset:160
	ds_read_b128 v[228:231], v222 offset:12960
	s_waitcnt lgkmcnt(7)
	v_mfma_f32_32x32x16_bf16 v[80:95], v[232:235], v[132:135], v[80:95]
	s_waitcnt lgkmcnt(5)
	v_mfma_f32_32x32x16_bf16 v[64:79], v[240:243], v[132:135], v[64:79]
	ds_read_b128 v[232:235], v222 offset:192
	ds_read_b128 v[240:243], v222 offset:12992
	v_mfma_f32_32x32x16_bf16 v[80:95], v[236:239], v[128:131], v[80:95]
	s_waitcnt lgkmcnt(6)
	v_mfma_f32_32x32x16_bf16 v[64:79], v[244:247], v[128:131], v[64:79]
	ds_read_b128 v[236:239], v222 offset:224
	ds_read_b128 v[244:247], v222 offset:13024
	s_waitcnt lgkmcnt(7)
	v_mfma_f32_32x32x16_bf16 v[80:95], v[248:251], v[124:127], v[80:95]
	s_waitcnt lgkmcnt(6)
	v_mfma_f32_32x32x16_bf16 v[64:79], v[166:169], v[124:127], v[64:79]
	ds_read_b128 v[166:169], v222 offset:256
	ds_read_b128 v[248:251], v222 offset:13056
	s_waitcnt lgkmcnt(7)
	v_mfma_f32_32x32x16_bf16 v[80:95], v[224:227], v[120:123], v[80:95]
	s_waitcnt lgkmcnt(6)
	v_mfma_f32_32x32x16_bf16 v[64:79], v[228:231], v[120:123], v[64:79]
	ds_read_b128 v[224:227], v222 offset:288
	ds_read_b128 v[228:231], v222 offset:13088
	s_waitcnt lgkmcnt(7)
	v_mfma_f32_32x32x16_bf16 v[80:95], v[232:235], v[116:119], v[80:95]
	s_waitcnt lgkmcnt(6)
	v_mfma_f32_32x32x16_bf16 v[64:79], v[240:243], v[116:119], v[64:79]
	ds_read_b128 v[232:235], v222 offset:320
	ds_read_b128 v[240:243], v222 offset:13120
	s_waitcnt lgkmcnt(7)
	v_mfma_f32_32x32x16_bf16 v[80:95], v[236:239], v[112:115], v[80:95]
	s_waitcnt lgkmcnt(6)
	v_mfma_f32_32x32x16_bf16 v[64:79], v[244:247], v[112:115], v[64:79]
	ds_read_b128 v[236:239], v222 offset:352
	ds_read_b128 v[244:247], v222 offset:13152
	s_waitcnt lgkmcnt(7)
	v_mfma_f32_32x32x16_bf16 v[80:95], v[166:169], v[108:111], v[80:95]
	s_waitcnt lgkmcnt(6)
	v_mfma_f32_32x32x16_bf16 v[64:79], v[248:251], v[108:111], v[64:79]
	s_waitcnt lgkmcnt(5)
	v_mfma_f32_32x32x16_bf16 v[80:95], v[224:227], v[104:107], v[80:95]
	s_waitcnt lgkmcnt(4)
	v_mfma_f32_32x32x16_bf16 v[64:79], v[228:231], v[104:107], v[64:79]
	s_waitcnt lgkmcnt(3)
	v_mfma_f32_32x32x16_bf16 v[80:95], v[232:235], v[100:103], v[80:95]
	s_waitcnt lgkmcnt(2)
	v_mfma_f32_32x32x16_bf16 v[64:79], v[240:243], v[100:103], v[64:79]
	s_waitcnt lgkmcnt(1)
	v_mfma_f32_32x32x16_bf16 v[80:95], v[236:239], v[96:99], v[80:95]
	s_waitcnt lgkmcnt(0)
	v_mfma_f32_32x32x16_bf16 v[64:79], v[244:247], v[96:99], v[64:79]
	s_nop 11
	v_max_f32_e32 v166, v81, v65
	v_max_f32_e32 v167, v82, v66
	v_max3_f32 v166, v80, v64, v166
	v_max_f32_e32 v168, v83, v67
	v_max3_f32 v166, v166, v167, v168
	v_max_f32_e32 v167, v84, v68
	v_max_f32_e32 v168, v85, v69
	v_max3_f32 v166, v166, v167, v168
	v_max_f32_e32 v167, v86, v70
	v_max_f32_e32 v168, v87, v71
	v_max3_f32 v166, v166, v167, v168
	v_max_f32_e32 v167, v88, v72
	v_max_f32_e32 v168, v89, v73
	v_max3_f32 v166, v166, v167, v168
	v_max_f32_e32 v167, v90, v74
	v_max_f32_e32 v168, v91, v75
	v_max3_f32 v166, v166, v167, v168
	v_max_f32_e32 v167, v92, v76
	v_max_f32_e32 v168, v93, v77
	v_max3_f32 v166, v166, v167, v168
	v_max_f32_e32 v167, v94, v78
	v_max_f32_e32 v168, v95, v79
	v_max3_f32 v166, v166, v167, v168
	v_mov_b32_e32 v167, v166
	s_nop 1
	v_permlane32_swap_b32_e32 v166, v167
	v_max_f32_e32 v222, v166, v167
	v_add_f32_e32 v166, 0x41000000, v223
	v_cmp_gt_f32_e32 vcc, v222, v166
	s_cbranch_vccz .LBB0_910
	s_nop 0
	v_cndmask_b32_e32 v222, v223, v222, vcc
	v_sub_f32_e32 v166, v223, v222
	v_exp_f32_e32 v223, v166
	s_and_saveexec_b64 s[0:1], s[38:39]
	ds_write_b32 v189, v223
	s_or_b64 exec, exec, s[0:1]
	v_mul_f32_e32 v191, v191, v223
	s_waitcnt lgkmcnt(0)
	v_add_u32_e32 v223, s12, v186
	ds_read_b128 v[166:169], v223
	ds_read_b128 v[224:227], v223 offset:32
	ds_read_b128 v[228:231], v223 offset:64
	ds_read_b128 v[232:235], v223 offset:96
	s_waitcnt lgkmcnt(0)
	s_waitcnt lgkmcnt(3)
	v_pk_mul_f32 v[2:3], v[2:3], v[168:169]
	s_waitcnt lgkmcnt(2)
	v_pk_mul_f32 v[4:5], v[4:5], v[224:225]
	s_waitcnt lgkmcnt(1)
	v_pk_mul_f32 v[8:9], v[8:9], v[228:229]
	s_waitcnt lgkmcnt(0)
	v_pk_mul_f32 v[12:13], v[12:13], v[232:233]
	v_pk_mul_f32 v[14:15], v[14:15], v[234:235]
	v_pk_mul_f32 v[10:11], v[10:11], v[230:231]
	v_pk_mul_f32 v[6:7], v[6:7], v[226:227]
	v_pk_mul_f32 v[0:1], v[0:1], v[166:167]
	v_pk_mul_f32 v[60:61], v[60:61], v[232:233]
	v_pk_mul_f32 v[56:57], v[56:57], v[228:229]
	v_pk_mul_f32 v[52:53], v[52:53], v[224:225]
	v_pk_mul_f32 v[62:63], v[62:63], v[234:235]
	v_pk_mul_f32 v[58:59], v[58:59], v[230:231]
	v_pk_mul_f32 v[54:55], v[54:55], v[226:227]
	v_pk_mul_f32 v[50:51], v[50:51], v[168:169]
	v_pk_mul_f32 v[48:49], v[48:49], v[166:167]
	v_pk_mul_f32 v[44:45], v[44:45], v[232:233]
	v_pk_mul_f32 v[40:41], v[40:41], v[228:229]
	v_pk_mul_f32 v[36:37], v[36:37], v[224:225]
	v_pk_mul_f32 v[46:47], v[46:47], v[234:235]
	v_pk_mul_f32 v[42:43], v[42:43], v[230:231]
	v_pk_mul_f32 v[38:39], v[38:39], v[226:227]
	v_pk_mul_f32 v[34:35], v[34:35], v[168:169]
	v_pk_mul_f32 v[32:33], v[32:33], v[166:167]
	v_pk_mul_f32 v[28:29], v[28:29], v[232:233]
	v_pk_mul_f32 v[24:25], v[24:25], v[228:229]
	v_pk_mul_f32 v[20:21], v[20:21], v[224:225]
	v_pk_mul_f32 v[30:31], v[30:31], v[234:235]
	v_pk_mul_f32 v[26:27], v[26:27], v[230:231]
	v_pk_mul_f32 v[22:23], v[22:23], v[226:227]
	v_pk_mul_f32 v[18:19], v[18:19], v[168:169]
	v_pk_mul_f32 v[16:17], v[16:17], v[166:167]
	s_branch .LBB0_911

; #define LAS __attribute__((address_space(3)))
; __device__ __forceinline__ int crow(int r, int hi) { return (r & 3) + 8 * (r >> 2) + 4 * hi; }
; #define MFMA32(a, b, c) __builtin_amdgcn_mfma_f32_32x32x16_bf16((a), (b), (c), 0, 0, 0)
; __device__ __forceinline__ void unit(LAS unsigned char* lds, const Tensors& T, int h, int qrow0, int nact, bool sample, int limbase, int kv0, int kvnew, int nt) {
;     ...
;         if (active && t <= lim) {
;             const LAS unsigned char* kp = lds + OFF_K + buf * KBUF + r32 * KP + hi * 16;
;             f32x16 p0, p1;
; #pragma unroll
;             for (int r = 0; r < 16; ++r) { p0[r] = 0.f; p1[r] = 0.f; }
;             { bf16x8 kf[4][2];
; #pragma unroll
;               for (int i = 0; i < 4; ++i) { kf[i][0] = *(const LAS bf16x8*)(kp + i * 32); kf[i][1] = *(const LAS bf16x8*)(kp + 32 * KP + i * 32); }
;               __builtin_amdgcn_sched_barrier(0);
; #pragma unroll
;               for (int i = 0; i < 12; ++i) {
;                   p0 = MFMA32(kf[i & 3][0], qf[i], p0); p1 = MFMA32(kf[i & 3][1], qf[i], p1);
;                   if (i + 4 < 12) { kf[i & 3][0] = *(const LAS bf16x8*)(kp + (i + 4) * 32); kf[i & 3][1] = *(const LAS bf16x8*)(kp + 32 * KP + (i + 4) * 32); }
;                   __builtin_amdgcn_sched_barrier(0);
;               } }
;             float rm = fmaxf(p0[0], p1[0]);
; #pragma unroll
;             for (int r = 1; r < 16; ++r) rm = fmaxf(rm, fmaxf(p0[r], p1[r]));
;             { const auto rr = __builtin_amdgcn_permlane32_swap(__float_as_uint(rm), __float_as_uint(rm), false, false);
;               rm = fmaxf(__uint_as_float(rr[0]), __uint_as_float(rr[1])); }
;             const bool need = rm > mrun + 8.0f;
;             if (__builtin_amdgcn_ballot_w64(need) != 0ull) {
;                 const float mn = need ? rm : mrun; const float alpha = __builtin_amdgcn_exp2f(mrun - mn); mrun = mn; lrun *= alpha;
;                 if (hi == 0) scr[r32] = alpha;
;                 asm volatile("s_waitcnt lgkmcnt(0)" ::: "memory");
; #pragma unroll
;                 for (int r = 0; r < 16; ++r) { const float f = scr[crow(r, hi)];
; #pragma unroll
;                     for (int d = 0; d < 4; ++d) o[d][r] *= f; }
;                 asm volatile("s_waitcnt lgkmcnt(0)" ::: "memory");
;             }
.LBB0_914:
	s_cmp_lt_i32 s8, 3
	s_cselect_b64 s[0:1], -1, 0
	s_or_b64 s[0:1], s[22:23], s[0:1]
	s_and_b64 vcc, exec, s[0:1]
	s_cbranch_vccnz .LBB0_926
	s_and_b32 s8, s13, 1
	s_mul_i32 s0, s8, 0x6400
	v_add_u32_e32 v164, s0, v221
	ds_read_b128 v[64:67], v164
	ds_read_b128 v[144:147], v164 offset:32
	ds_read_b128 v[68:71], v164 offset:12800
	ds_read_b128 v[148:151], v164 offset:12832
	ds_read_b128 v[152:155], v164 offset:64
	ds_read_b128 v[156:159], v164 offset:96
	ds_read_b128 v[160:163], v164 offset:12864
	ds_read_b128 v[192:195], v164 offset:12896
	s_waitcnt lgkmcnt(7)
	v_mfma_f32_32x32x16_bf16 v[80:95], v[64:67], v[140:143], 0
	s_waitcnt lgkmcnt(5)
	v_mfma_f32_32x32x16_bf16 v[64:79], v[68:71], v[140:143], 0
	ds_read_b128 v[140:143], v164 offset:128
	ds_read_b128 v[196:199], v164 offset:12928
	v_mfma_f32_32x32x16_bf16 v[80:95], v[144:147], v[136:139], v[80:95]
	s_waitcnt lgkmcnt(6)
	v_mfma_f32_32x32x16_bf16 v[64:79], v[148:151], v[136:139], v[64:79]
	ds_read_b128 v[136:139], v164 offset:160
	ds_read_b128 v[144:147], v164 offset:12960
	s_waitcnt lgkmcnt(7)
	v_mfma_f32_32x32x16_bf16 v[80:95], v[152:155], v[132:135], v[80:95]
	s_waitcnt lgkmcnt(5)
	v_mfma_f32_32x32x16_bf16 v[64:79], v[160:163], v[132:135], v[64:79]
	ds_read_b128 v[132:135], v164 offset:192
	ds_read_b128 v[148:151], v164 offset:12992
	v_mfma_f32_32x32x16_bf16 v[80:95], v[156:159], v[128:131], v[80:95]
	s_waitcnt lgkmcnt(6)
	v_mfma_f32_32x32x16_bf16 v[64:79], v[192:195], v[128:131], v[64:79]
	ds_read_b128 v[128:131], v164 offset:224
	ds_read_b128 v[152:155], v164 offset:13024
	s_waitcnt lgkmcnt(7)
	v_mfma_f32_32x32x16_bf16 v[80:95], v[140:143], v[124:127], v[80:95]
	s_waitcnt lgkmcnt(6)
	v_mfma_f32_32x32x16_bf16 v[64:79], v[196:199], v[124:127], v[64:79]
	ds_read_b128 v[124:127], v164 offset:256
	ds_read_b128 v[140:143], v164 offset:13056
	s_waitcnt lgkmcnt(7)
	v_mfma_f32_32x32x16_bf16 v[80:95], v[136:139], v[120:123], v[80:95]
	s_waitcnt lgkmcnt(6)
	v_mfma_f32_32x32x16_bf16 v[64:79], v[144:147], v[120:123], v[64:79]
	ds_read_b128 v[120:123], v164 offset:288
	ds_read_b128 v[136:139], v164 offset:13088
	s_waitcnt lgkmcnt(7)
	v_mfma_f32_32x32x16_bf16 v[80:95], v[132:135], v[116:119], v[80:95]
	s_waitcnt lgkmcnt(6)
	v_mfma_f32_32x32x16_bf16 v[64:79], v[148:151], v[116:119], v[64:79]
	ds_read_b128 v[116:119], v164 offset:320
	ds_read_b128 v[132:135], v164 offset:13120
	s_waitcnt lgkmcnt(7)
	v_mfma_f32_32x32x16_bf16 v[80:95], v[128:131], v[112:115], v[80:95]
	s_waitcnt lgkmcnt(6)
	v_mfma_f32_32x32x16_bf16 v[64:79], v[152:155], v[112:115], v[64:79]
	ds_read_b128 v[112:115], v164 offset:352
	ds_read_b128 v[128:131], v164 offset:13152
	s_waitcnt lgkmcnt(7)
	v_mfma_f32_32x32x16_bf16 v[80:95], v[124:127], v[108:111], v[80:95]
	s_waitcnt lgkmcnt(6)
	v_mfma_f32_32x32x16_bf16 v[64:79], v[140:143], v[108:111], v[64:79]
	s_waitcnt lgkmcnt(5)
	v_mfma_f32_32x32x16_bf16 v[80:95], v[120:123], v[104:107], v[80:95]
	s_waitcnt lgkmcnt(4)
	v_mfma_f32_32x32x16_bf16 v[64:79], v[136:139], v[104:107], v[64:79]
	s_waitcnt lgkmcnt(3)
	v_mfma_f32_32x32x16_bf16 v[80:95], v[116:119], v[100:103], v[80:95]
	s_waitcnt lgkmcnt(2)
	v_mfma_f32_32x32x16_bf16 v[64:79], v[132:135], v[100:103], v[64:79]
	s_waitcnt lgkmcnt(1)
	v_mfma_f32_32x32x16_bf16 v[80:95], v[112:115], v[96:99], v[80:95]
	s_waitcnt lgkmcnt(0)
	v_mfma_f32_32x32x16_bf16 v[64:79], v[128:131], v[96:99], v[64:79]
	s_nop 11
	v_max_f32_e32 v96, v81, v65
	v_max_f32_e32 v97, v82, v66
	v_max3_f32 v96, v80, v64, v96
	v_max_f32_e32 v98, v83, v67
	v_max3_f32 v96, v96, v97, v98
	v_max_f32_e32 v97, v84, v68
	v_max_f32_e32 v98, v85, v69
	v_max3_f32 v96, v96, v97, v98
	v_max_f32_e32 v97, v86, v70
	v_max_f32_e32 v98, v87, v71
	v_max3_f32 v96, v96, v97, v98
	v_max_f32_e32 v97, v88, v72
	v_max_f32_e32 v98, v89, v73
	v_max3_f32 v96, v96, v97, v98
	v_max_f32_e32 v97, v90, v74
	v_max_f32_e32 v98, v91, v75
	v_max3_f32 v96, v96, v97, v98
	v_max_f32_e32 v97, v92, v76
	v_max_f32_e32 v98, v93, v77
	v_max3_f32 v96, v96, v97, v98
	v_max_f32_e32 v97, v94, v78
	v_max_f32_e32 v98, v95, v79
	v_max3_f32 v96, v96, v97, v98
	v_mov_b32_e32 v97, v96
	s_nop 1
	v_permlane32_swap_b32_e32 v96, v97
	v_max_f32_e32 v96, v96, v97
	v_add_f32_e32 v97, 0x41000000, v222
	v_cmp_gt_f32_e32 vcc, v96, v97
	s_cbranch_vccz .LBB0_924
	s_nop 0
	v_cndmask_b32_e32 v96, v222, v96, vcc
	v_sub_f32_e32 v97, v222, v96
	v_exp_f32_e32 v97, v97
	s_and_saveexec_b64 s[0:1], s[38:39]
	ds_write_b32 v189, v97
	s_or_b64 exec, exec, s[0:1]
	v_mul_f32_e32 v191, v191, v97
	s_waitcnt lgkmcnt(0)
	v_add_u32_e32 v97, s12, v186
	ds_read_b128 v[98:101], v97
	ds_read_b128 v[102:105], v97 offset:32
	ds_read_b128 v[106:109], v97 offset:64
	ds_read_b128 v[110:113], v97 offset:96
	s_waitcnt lgkmcnt(0)
	s_waitcnt lgkmcnt(3)
	v_pk_mul_f32 v[2:3], v[2:3], v[100:101]
	s_waitcnt lgkmcnt(2)
	v_pk_mul_f32 v[4:5], v[4:5], v[102:103]
	s_waitcnt lgkmcnt(1)
	v_pk_mul_f32 v[8:9], v[8:9], v[106:107]
	s_waitcnt lgkmcnt(0)
	v_pk_mul_f32 v[12:13], v[12:13], v[110:111]
	v_pk_mul_f32 v[14:15], v[14:15], v[112:113]
	v_pk_mul_f32 v[10:11], v[10:11], v[108:109]
	v_pk_mul_f32 v[6:7], v[6:7], v[104:105]
	v_pk_mul_f32 v[0:1], v[0:1], v[98:99]
	v_pk_mul_f32 v[60:61], v[60:61], v[110:111]
	v_pk_mul_f32 v[56:57], v[56:57], v[106:107]
	v_pk_mul_f32 v[52:53], v[52:53], v[102:103]
	v_pk_mul_f32 v[62:63], v[62:63], v[112:113]
	v_pk_mul_f32 v[58:59], v[58:59], v[108:109]
	v_pk_mul_f32 v[54:55], v[54:55], v[104:105]
	v_pk_mul_f32 v[50:51], v[50:51], v[100:101]
	v_pk_mul_f32 v[48:49], v[48:49], v[98:99]
	v_pk_mul_f32 v[44:45], v[44:45], v[110:111]
	v_pk_mul_f32 v[40:41], v[40:41], v[106:107]
	v_pk_mul_f32 v[36:37], v[36:37], v[102:103]
	v_pk_mul_f32 v[46:47], v[46:47], v[112:113]
	v_pk_mul_f32 v[42:43], v[42:43], v[108:109]
	v_pk_mul_f32 v[38:39], v[38:39], v[104:105]
	v_pk_mul_f32 v[34:35], v[34:35], v[100:101]
	v_pk_mul_f32 v[32:33], v[32:33], v[98:99]
	v_pk_mul_f32 v[28:29], v[28:29], v[110:111]
	v_pk_mul_f32 v[24:25], v[24:25], v[106:107]
	v_pk_mul_f32 v[20:21], v[20:21], v[102:103]
	v_pk_mul_f32 v[30:31], v[30:31], v[112:113]
	v_pk_mul_f32 v[26:27], v[26:27], v[108:109]
	v_pk_mul_f32 v[22:23], v[22:23], v[104:105]
	v_pk_mul_f32 v[18:19], v[18:19], v[100:101]
	v_pk_mul_f32 v[16:17], v[16:17], v[98:99]
	s_branch .LBB0_925
